# P3: double-buffered cross-chunk scan loop + attention/scan role remap (176 WGs: 2 scan + 6 attention waves; 64 WGs: 3 + 5) so a wave runs at most 3 attention units
# baseline (speedup 1.0000x reference)
; __device__ __forceinline__ u32x2 pk4(f32x4 v) { u32x2 w; w.x = cvt_pk_bf16(v[0], v[1]); w.y = cvt_pk_bf16(v[2], v[3]); return w; }
; __device__ __forceinline__ f32x4 up4(u32x2 w) { return (f32x4){bf_lo(w.x), bf_hi(w.x), bf_lo(w.y), bf_hi(w.y)}; }
; template <bool DRYS = false>
; __device__ __forceinline__ void scan_phase(const Args& a, int tid, int nthr, int blk, int nblk) {
;     ...
;     for (int q = tid; q < per; q += nthr) {
;     const int p = blk * per + q; if (p >= 32768) break;
;     const int hh = p >> 13, dv = (p >> 5) & 255, dq = p & 31; f32x4 st = (f32x4){0.f, 0.f, 0.f, 0.f};
;     u32x2* up = US64 + (size_t)hh * 8192 + dv * 32 + dq; const f32x4* dp = DEC + hh * 32 + dq;
;     for (int c0 = 0; c0 < 256; c0 += 8) { u32x2 u[8]; f32x4 d[8];
; #pragma unroll
;         for (int j = 0; j < 8; ++j) { u[j] = up[(size_t)(c0 + j) * 32768]; d[j] = dp[(c0 + j) * 128]; }
; #pragma unroll
;         for (int j = 0; j < 8; ++j) { if (!DRYS || st[0] == 123.456f) up[(size_t)(c0 + j) * 32768] = pk4(st); st = d[j] * st + up4(u[j]); } }
.LBB0_566:
	v_add_u32_e32 v4, s27, v7
	v_cmp_gt_i32_e32 vcc, s28, v4
	s_or_b64 s[20:21], s[20:21], exec
	s_and_saveexec_b64 s[24:25], vcc
	s_cbranch_execz .LBB0_565
	v_ashrrev_i32_e32 v8, 13, v4
	v_ashrrev_i32_e32 v9, 31, v8
	v_lshlrev_b64 v[10:11], 16, v[8:9]
	v_lshlrev_b32_e32 v12, 5, v8
	v_lshlrev_b32_e32 v14, 3, v1
	v_ashrrev_i32_e32 v13, 31, v12
	v_or_b32_e32 v9, v6, v10
	v_lshlrev_b64 v[12:13], 4, v[12:13]
	v_and_or_b32 v10, v14, s29, v9
	v_mov_b32_e32 v14, 0
	v_or_b32_e32 v12, v2, v12
	s_mov_b32 s30, -8
	v_mov_b32_e32 v15, v14
	v_mov_b32_e32 v16, v14
	v_mov_b32_e32 v17, v14
	s_mov_b64 s[98:99], s[52:53]
	s_add_u32 s100, s52, 0x4110000
	s_addc_u32 s101, s53, 0
	s_mov_b64 s[30:31], s[52:53]
	global_load_dwordx2 v[18:19], v10, s[98:99]
	s_add_u32 s98, s98, 0x40000
	s_addc_u32 s99, s99, 0
	global_load_dwordx4 v[34:37], v12, s[100:101]
	global_load_dwordx2 v[20:21], v10, s[98:99]
	s_add_u32 s98, s98, 0x40000
	s_addc_u32 s99, s99, 0
	global_load_dwordx4 v[38:41], v12, s[100:101] offset:2048
	s_add_u32 s100, s100, 0x1000
	s_addc_u32 s101, s101, 0
	global_load_dwordx2 v[22:23], v10, s[98:99]
	s_add_u32 s98, s98, 0x40000
	s_addc_u32 s99, s99, 0
	global_load_dwordx4 v[42:45], v12, s[100:101]
	global_load_dwordx2 v[24:25], v10, s[98:99]
	s_add_u32 s98, s98, 0x40000
	s_addc_u32 s99, s99, 0
	global_load_dwordx4 v[46:49], v12, s[100:101] offset:2048
	s_add_u32 s100, s100, 0x1000
	s_addc_u32 s101, s101, 0
	global_load_dwordx2 v[26:27], v10, s[98:99]
	s_add_u32 s98, s98, 0x40000
	s_addc_u32 s99, s99, 0
	global_load_dwordx4 v[50:53], v12, s[100:101]
	global_load_dwordx2 v[28:29], v10, s[98:99]
	s_add_u32 s98, s98, 0x40000
	s_addc_u32 s99, s99, 0
	global_load_dwordx4 v[54:57], v12, s[100:101] offset:2048
	s_add_u32 s100, s100, 0x1000
	s_addc_u32 s101, s101, 0
	global_load_dwordx2 v[30:31], v10, s[98:99]
	s_add_u32 s98, s98, 0x40000
	s_addc_u32 s99, s99, 0
	global_load_dwordx4 v[58:61], v12, s[100:101]
	global_load_dwordx2 v[32:33], v10, s[98:99]
	s_add_u32 s98, s98, 0x40000
	s_addc_u32 s99, s99, 0
	global_load_dwordx4 v[62:65], v12, s[100:101] offset:2048
	s_add_u32 s100, s100, 0x1000
	s_addc_u32 s101, s101, 0
	s_movk_i32 vcc_lo, 15
.Lsc_loop:
	global_load_dwordx2 v[66:67], v10, s[98:99]
	s_add_u32 s98, s98, 0x40000
	s_addc_u32 s99, s99, 0
	global_load_dwordx4 v[84:87], v12, s[100:101]
	global_load_dwordx2 v[68:69], v10, s[98:99]
	s_add_u32 s98, s98, 0x40000
	s_addc_u32 s99, s99, 0
	global_load_dwordx4 v[88:91], v12, s[100:101] offset:2048
	s_add_u32 s100, s100, 0x1000
	s_addc_u32 s101, s101, 0
	global_load_dwordx2 v[70:71], v10, s[98:99]
	s_add_u32 s98, s98, 0x40000
	s_addc_u32 s99, s99, 0
	global_load_dwordx4 v[92:95], v12, s[100:101]
	global_load_dwordx2 v[72:73], v10, s[98:99]
	s_add_u32 s98, s98, 0x40000
	s_addc_u32 s99, s99, 0
	global_load_dwordx4 v[96:99], v12, s[100:101] offset:2048
	s_add_u32 s100, s100, 0x1000
	s_addc_u32 s101, s101, 0
	global_load_dwordx2 v[74:75], v10, s[98:99]
	s_add_u32 s98, s98, 0x40000
	s_addc_u32 s99, s99, 0
	global_load_dwordx4 v[100:103], v12, s[100:101]
	global_load_dwordx2 v[76:77], v10, s[98:99]
	s_add_u32 s98, s98, 0x40000
	s_addc_u32 s99, s99, 0
	global_load_dwordx4 v[104:107], v12, s[100:101] offset:2048
	s_add_u32 s100, s100, 0x1000
	s_addc_u32 s101, s101, 0
	global_load_dwordx2 v[78:79], v10, s[98:99]
	s_add_u32 s98, s98, 0x40000
	s_addc_u32 s99, s99, 0
	global_load_dwordx4 v[108:111], v12, s[100:101]
	global_load_dwordx2 v[80:81], v10, s[98:99]
	s_add_u32 s98, s98, 0x40000
	s_addc_u32 s99, s99, 0
	global_load_dwordx4 v[112:115], v12, s[100:101] offset:2048
	s_add_u32 s100, s100, 0x1000
	s_addc_u32 s101, s101, 0
	v_cvt_pk_bf16_f32 v82, v14, v15
	v_cvt_pk_bf16_f32 v83, v16, v17
	global_store_dwordx2 v10, v[82:83], s[30:31]
	s_add_u32 s30, s30, 0x40000
	s_addc_u32 s31, s31, 0
	s_waitcnt vmcnt(31)
	v_lshlrev_b32_e32 v116, 16, v18
	v_and_b32_e32 v117, 0xffff0000, v18
	v_lshlrev_b32_e32 v118, 16, v19
	v_and_b32_e32 v119, 0xffff0000, v19
	v_pk_fma_f32 v[16:17], v[16:17], v[36:37], v[118:119]
	v_pk_fma_f32 v[14:15], v[14:15], v[34:35], v[116:117]
	v_cvt_pk_bf16_f32 v124, v14, v15
	v_cvt_pk_bf16_f32 v125, v16, v17
	global_store_dwordx2 v10, v[124:125], s[30:31]
	s_add_u32 s30, s30, 0x40000
	s_addc_u32 s31, s31, 0
	s_waitcnt vmcnt(30)
	v_lshlrev_b32_e32 v120, 16, v20
	v_and_b32_e32 v121, 0xffff0000, v20
	v_lshlrev_b32_e32 v122, 16, v21
	v_and_b32_e32 v123, 0xffff0000, v21
	v_pk_fma_f32 v[16:17], v[16:17], v[40:41], v[122:123]
	v_pk_fma_f32 v[14:15], v[14:15], v[38:39], v[120:121]
	v_cvt_pk_bf16_f32 v82, v14, v15
	v_cvt_pk_bf16_f32 v83, v16, v17
	global_store_dwordx2 v10, v[82:83], s[30:31]
	s_add_u32 s30, s30, 0x40000
	s_addc_u32 s31, s31, 0
	s_waitcnt vmcnt(29)
	v_lshlrev_b32_e32 v116, 16, v22
	v_and_b32_e32 v117, 0xffff0000, v22
	v_lshlrev_b32_e32 v118, 16, v23
	v_and_b32_e32 v119, 0xffff0000, v23
	v_pk_fma_f32 v[16:17], v[16:17], v[44:45], v[118:119]
	v_pk_fma_f32 v[14:15], v[14:15], v[42:43], v[116:117]
	v_cvt_pk_bf16_f32 v124, v14, v15
	v_cvt_pk_bf16_f32 v125, v16, v17
	global_store_dwordx2 v10, v[124:125], s[30:31]
	s_add_u32 s30, s30, 0x40000
	s_addc_u32 s31, s31, 0
	s_waitcnt vmcnt(28)
	v_lshlrev_b32_e32 v120, 16, v24
	v_and_b32_e32 v121, 0xffff0000, v24
	v_lshlrev_b32_e32 v122, 16, v25
	v_and_b32_e32 v123, 0xffff0000, v25
	v_pk_fma_f32 v[16:17], v[16:17], v[48:49], v[122:123]
	v_pk_fma_f32 v[14:15], v[14:15], v[46:47], v[120:121]
	v_cvt_pk_bf16_f32 v82, v14, v15
	v_cvt_pk_bf16_f32 v83, v16, v17
	global_store_dwordx2 v10, v[82:83], s[30:31]
	s_add_u32 s30, s30, 0x40000
	s_addc_u32 s31, s31, 0
	s_waitcnt vmcnt(27)
; __device__ __forceinline__ u32x2 pk4(f32x4 v) { u32x2 w; w.x = cvt_pk_bf16(v[0], v[1]); w.y = cvt_pk_bf16(v[2], v[3]); return w; }
; __device__ __forceinline__ f32x4 up4(u32x2 w) { return (f32x4){bf_lo(w.x), bf_hi(w.x), bf_lo(w.y), bf_hi(w.y)}; }
; template <bool DRYS = false>
; __device__ __forceinline__ void scan_phase(const Args& a, int tid, int nthr, int blk, int nblk) {
;     ...
;     for (int c0 = 0; c0 < 256; c0 += 8) { u32x2 u[8]; f32x4 d[8];
; #pragma unroll
;         for (int j = 0; j < 8; ++j) { u[j] = up[(size_t)(c0 + j) * 32768]; d[j] = dp[(c0 + j) * 128]; }
; #pragma unroll
;         for (int j = 0; j < 8; ++j) { if (!DRYS || st[0] == 123.456f) up[(size_t)(c0 + j) * 32768] = pk4(st); st = d[j] * st + up4(u[j]); } }
	v_lshlrev_b32_e32 v116, 16, v26
	v_and_b32_e32 v117, 0xffff0000, v26
	v_lshlrev_b32_e32 v118, 16, v27
	v_and_b32_e32 v119, 0xffff0000, v27
	v_pk_fma_f32 v[16:17], v[16:17], v[52:53], v[118:119]
	v_pk_fma_f32 v[14:15], v[14:15], v[50:51], v[116:117]
	v_cvt_pk_bf16_f32 v124, v14, v15
	v_cvt_pk_bf16_f32 v125, v16, v17
	global_store_dwordx2 v10, v[124:125], s[30:31]
	s_add_u32 s30, s30, 0x40000
	s_addc_u32 s31, s31, 0
	s_waitcnt vmcnt(26)
	v_lshlrev_b32_e32 v120, 16, v28
	v_and_b32_e32 v121, 0xffff0000, v28
	v_lshlrev_b32_e32 v122, 16, v29
	v_and_b32_e32 v123, 0xffff0000, v29
	v_pk_fma_f32 v[16:17], v[16:17], v[56:57], v[122:123]
	v_pk_fma_f32 v[14:15], v[14:15], v[54:55], v[120:121]
	v_cvt_pk_bf16_f32 v82, v14, v15
	v_cvt_pk_bf16_f32 v83, v16, v17
	global_store_dwordx2 v10, v[82:83], s[30:31]
	s_add_u32 s30, s30, 0x40000
	s_addc_u32 s31, s31, 0
	s_waitcnt vmcnt(25)
	v_lshlrev_b32_e32 v116, 16, v30
	v_and_b32_e32 v117, 0xffff0000, v30
	v_lshlrev_b32_e32 v118, 16, v31
	v_and_b32_e32 v119, 0xffff0000, v31
	v_pk_fma_f32 v[16:17], v[16:17], v[60:61], v[118:119]
	v_pk_fma_f32 v[14:15], v[14:15], v[58:59], v[116:117]
	v_cvt_pk_bf16_f32 v124, v14, v15
	v_cvt_pk_bf16_f32 v125, v16, v17
	global_store_dwordx2 v10, v[124:125], s[30:31]
	s_add_u32 s30, s30, 0x40000
	s_addc_u32 s31, s31, 0
	s_waitcnt vmcnt(24)
	v_lshlrev_b32_e32 v120, 16, v32
	v_and_b32_e32 v121, 0xffff0000, v32
	v_lshlrev_b32_e32 v122, 16, v33
	v_and_b32_e32 v123, 0xffff0000, v33
	v_pk_fma_f32 v[16:17], v[16:17], v[64:65], v[122:123]
	v_pk_fma_f32 v[14:15], v[14:15], v[62:63], v[120:121]
	s_cmp_eq_u32 vcc_lo, 0
	s_cbranch_scc1 .Lsc_final
	global_load_dwordx2 v[18:19], v10, s[98:99]
	s_add_u32 s98, s98, 0x40000
	s_addc_u32 s99, s99, 0
	global_load_dwordx4 v[34:37], v12, s[100:101]
	global_load_dwordx2 v[20:21], v10, s[98:99]
	s_add_u32 s98, s98, 0x40000
	s_addc_u32 s99, s99, 0
	global_load_dwordx4 v[38:41], v12, s[100:101] offset:2048
	s_add_u32 s100, s100, 0x1000
	s_addc_u32 s101, s101, 0
	global_load_dwordx2 v[22:23], v10, s[98:99]
	s_add_u32 s98, s98, 0x40000
	s_addc_u32 s99, s99, 0
	global_load_dwordx4 v[42:45], v12, s[100:101]
	global_load_dwordx2 v[24:25], v10, s[98:99]
	s_add_u32 s98, s98, 0x40000
	s_addc_u32 s99, s99, 0
	global_load_dwordx4 v[46:49], v12, s[100:101] offset:2048
	s_add_u32 s100, s100, 0x1000
	s_addc_u32 s101, s101, 0
	global_load_dwordx2 v[26:27], v10, s[98:99]
	s_add_u32 s98, s98, 0x40000
	s_addc_u32 s99, s99, 0
	global_load_dwordx4 v[50:53], v12, s[100:101]
	global_load_dwordx2 v[28:29], v10, s[98:99]
	s_add_u32 s98, s98, 0x40000
	s_addc_u32 s99, s99, 0
	global_load_dwordx4 v[54:57], v12, s[100:101] offset:2048
	s_add_u32 s100, s100, 0x1000
	s_addc_u32 s101, s101, 0
	global_load_dwordx2 v[30:31], v10, s[98:99]
	s_add_u32 s98, s98, 0x40000
	s_addc_u32 s99, s99, 0
	global_load_dwordx4 v[58:61], v12, s[100:101]
	global_load_dwordx2 v[32:33], v10, s[98:99]
	s_add_u32 s98, s98, 0x40000
	s_addc_u32 s99, s99, 0
	global_load_dwordx4 v[62:65], v12, s[100:101] offset:2048
	s_add_u32 s100, s100, 0x1000
	s_addc_u32 s101, s101, 0
	v_cvt_pk_bf16_f32 v82, v14, v15
	v_cvt_pk_bf16_f32 v83, v16, v17
	global_store_dwordx2 v10, v[82:83], s[30:31]
	s_add_u32 s30, s30, 0x40000
	s_addc_u32 s31, s31, 0
	s_waitcnt vmcnt(31)
	v_lshlrev_b32_e32 v116, 16, v66
	v_and_b32_e32 v117, 0xffff0000, v66
	v_lshlrev_b32_e32 v118, 16, v67
	v_and_b32_e32 v119, 0xffff0000, v67
	v_pk_fma_f32 v[16:17], v[16:17], v[86:87], v[118:119]
	v_pk_fma_f32 v[14:15], v[14:15], v[84:85], v[116:117]
	v_cvt_pk_bf16_f32 v124, v14, v15
	v_cvt_pk_bf16_f32 v125, v16, v17
	global_store_dwordx2 v10, v[124:125], s[30:31]
	s_add_u32 s30, s30, 0x40000
	s_addc_u32 s31, s31, 0
	s_waitcnt vmcnt(30)
	v_lshlrev_b32_e32 v120, 16, v68
	v_and_b32_e32 v121, 0xffff0000, v68
	v_lshlrev_b32_e32 v122, 16, v69
	v_and_b32_e32 v123, 0xffff0000, v69
	v_pk_fma_f32 v[16:17], v[16:17], v[90:91], v[122:123]
	v_pk_fma_f32 v[14:15], v[14:15], v[88:89], v[120:121]
	v_cvt_pk_bf16_f32 v82, v14, v15
	v_cvt_pk_bf16_f32 v83, v16, v17
	global_store_dwordx2 v10, v[82:83], s[30:31]
	s_add_u32 s30, s30, 0x40000
	s_addc_u32 s31, s31, 0
	s_waitcnt vmcnt(29)
	v_lshlrev_b32_e32 v116, 16, v70
	v_and_b32_e32 v117, 0xffff0000, v70
	v_lshlrev_b32_e32 v118, 16, v71
	v_and_b32_e32 v119, 0xffff0000, v71
	v_pk_fma_f32 v[16:17], v[16:17], v[94:95], v[118:119]
	v_pk_fma_f32 v[14:15], v[14:15], v[92:93], v[116:117]
	v_cvt_pk_bf16_f32 v124, v14, v15
	v_cvt_pk_bf16_f32 v125, v16, v17
	global_store_dwordx2 v10, v[124:125], s[30:31]
	s_add_u32 s30, s30, 0x40000
	s_addc_u32 s31, s31, 0
	s_waitcnt vmcnt(28)
	v_lshlrev_b32_e32 v120, 16, v72
	v_and_b32_e32 v121, 0xffff0000, v72
	v_lshlrev_b32_e32 v122, 16, v73
	v_and_b32_e32 v123, 0xffff0000, v73
	v_pk_fma_f32 v[16:17], v[16:17], v[98:99], v[122:123]
	v_pk_fma_f32 v[14:15], v[14:15], v[96:97], v[120:121]
	v_cvt_pk_bf16_f32 v82, v14, v15
	v_cvt_pk_bf16_f32 v83, v16, v17
	global_store_dwordx2 v10, v[82:83], s[30:31]
	s_add_u32 s30, s30, 0x40000
	s_addc_u32 s31, s31, 0
	s_waitcnt vmcnt(27)
	v_lshlrev_b32_e32 v116, 16, v74
	v_and_b32_e32 v117, 0xffff0000, v74
	v_lshlrev_b32_e32 v118, 16, v75
	v_and_b32_e32 v119, 0xffff0000, v75
	v_pk_fma_f32 v[16:17], v[16:17], v[102:103], v[118:119]
	v_pk_fma_f32 v[14:15], v[14:15], v[100:101], v[116:117]
	v_cvt_pk_bf16_f32 v124, v14, v15
	v_cvt_pk_bf16_f32 v125, v16, v17
	global_store_dwordx2 v10, v[124:125], s[30:31]
	s_add_u32 s30, s30, 0x40000
	s_addc_u32 s31, s31, 0
	s_waitcnt vmcnt(26)
	v_lshlrev_b32_e32 v120, 16, v76
	v_and_b32_e32 v121, 0xffff0000, v76
	v_lshlrev_b32_e32 v122, 16, v77
	v_and_b32_e32 v123, 0xffff0000, v77
	v_pk_fma_f32 v[16:17], v[16:17], v[106:107], v[122:123]
	v_pk_fma_f32 v[14:15], v[14:15], v[104:105], v[120:121]
	v_cvt_pk_bf16_f32 v82, v14, v15
	v_cvt_pk_bf16_f32 v83, v16, v17
	global_store_dwordx2 v10, v[82:83], s[30:31]
	s_add_u32 s30, s30, 0x40000
	s_addc_u32 s31, s31, 0
	s_waitcnt vmcnt(25)
	v_lshlrev_b32_e32 v116, 16, v78
	v_and_b32_e32 v117, 0xffff0000, v78
	v_lshlrev_b32_e32 v118, 16, v79
	v_and_b32_e32 v119, 0xffff0000, v79
	v_pk_fma_f32 v[16:17], v[16:17], v[110:111], v[118:119]
	v_pk_fma_f32 v[14:15], v[14:15], v[108:109], v[116:117]
	v_cvt_pk_bf16_f32 v124, v14, v15
	v_cvt_pk_bf16_f32 v125, v16, v17
	global_store_dwordx2 v10, v[124:125], s[30:31]
	s_add_u32 s30, s30, 0x40000
	s_addc_u32 s31, s31, 0
	s_waitcnt vmcnt(24)
	v_lshlrev_b32_e32 v120, 16, v80
	v_and_b32_e32 v121, 0xffff0000, v80
	v_lshlrev_b32_e32 v122, 16, v81
	v_and_b32_e32 v123, 0xffff0000, v81
	v_pk_fma_f32 v[16:17], v[16:17], v[114:115], v[122:123]
	v_pk_fma_f32 v[14:15], v[14:15], v[112:113], v[120:121]
	s_sub_u32 vcc_lo, vcc_lo, 1
	s_branch .Lsc_loop
; __device__ __forceinline__ u32x2 pk4(f32x4 v) { u32x2 w; w.x = cvt_pk_bf16(v[0], v[1]); w.y = cvt_pk_bf16(v[2], v[3]); return w; }
; __device__ __forceinline__ f32x4 up4(u32x2 w) { return (f32x4){bf_lo(w.x), bf_hi(w.x), bf_lo(w.y), bf_hi(w.y)}; }
; template <bool DRYS = false>
; __device__ __forceinline__ void scan_phase(const Args& a, int tid, int nthr, int blk, int nblk) {
;     ...
;     for (int c0 = 0; c0 < 256; c0 += 8) { u32x2 u[8]; f32x4 d[8];
; #pragma unroll
;         for (int j = 0; j < 8; ++j) { u[j] = up[(size_t)(c0 + j) * 32768]; d[j] = dp[(c0 + j) * 128]; }
; #pragma unroll
;         for (int j = 0; j < 8; ++j) { if (!DRYS || st[0] == 123.456f) up[(size_t)(c0 + j) * 32768] = pk4(st); st = d[j] * st + up4(u[j]); } }
;     float* so = a.out + O_SP + (size_t)(hh * 128 + 4 * dq) * 256 + dv;
;     if (!DRYS || st[0] == 123.456f) { so[0] = st[0]; so[256] = st[1]; so[512] = st[2]; so[768] = st[3]; }
;     }
.Lsc_final:
	v_cvt_pk_bf16_f32 v82, v14, v15
	v_cvt_pk_bf16_f32 v83, v16, v17
	global_store_dwordx2 v10, v[82:83], s[30:31]
	s_add_u32 s30, s30, 0x40000
	s_addc_u32 s31, s31, 0
	s_waitcnt vmcnt(15)
	v_lshlrev_b32_e32 v116, 16, v66
	v_and_b32_e32 v117, 0xffff0000, v66
	v_lshlrev_b32_e32 v118, 16, v67
	v_and_b32_e32 v119, 0xffff0000, v67
	v_pk_fma_f32 v[16:17], v[16:17], v[86:87], v[118:119]
	v_pk_fma_f32 v[14:15], v[14:15], v[84:85], v[116:117]
	v_cvt_pk_bf16_f32 v124, v14, v15
	v_cvt_pk_bf16_f32 v125, v16, v17
	global_store_dwordx2 v10, v[124:125], s[30:31]
	s_add_u32 s30, s30, 0x40000
	s_addc_u32 s31, s31, 0
	s_waitcnt vmcnt(14)
	v_lshlrev_b32_e32 v120, 16, v68
	v_and_b32_e32 v121, 0xffff0000, v68
	v_lshlrev_b32_e32 v122, 16, v69
	v_and_b32_e32 v123, 0xffff0000, v69
	v_pk_fma_f32 v[16:17], v[16:17], v[90:91], v[122:123]
	v_pk_fma_f32 v[14:15], v[14:15], v[88:89], v[120:121]
	v_cvt_pk_bf16_f32 v82, v14, v15
	v_cvt_pk_bf16_f32 v83, v16, v17
	global_store_dwordx2 v10, v[82:83], s[30:31]
	s_add_u32 s30, s30, 0x40000
	s_addc_u32 s31, s31, 0
	s_waitcnt vmcnt(13)
	v_lshlrev_b32_e32 v116, 16, v70
	v_and_b32_e32 v117, 0xffff0000, v70
	v_lshlrev_b32_e32 v118, 16, v71
	v_and_b32_e32 v119, 0xffff0000, v71
	v_pk_fma_f32 v[16:17], v[16:17], v[94:95], v[118:119]
	v_pk_fma_f32 v[14:15], v[14:15], v[92:93], v[116:117]
	v_cvt_pk_bf16_f32 v124, v14, v15
	v_cvt_pk_bf16_f32 v125, v16, v17
	global_store_dwordx2 v10, v[124:125], s[30:31]
	s_add_u32 s30, s30, 0x40000
	s_addc_u32 s31, s31, 0
	s_waitcnt vmcnt(12)
	v_lshlrev_b32_e32 v120, 16, v72
	v_and_b32_e32 v121, 0xffff0000, v72
	v_lshlrev_b32_e32 v122, 16, v73
	v_and_b32_e32 v123, 0xffff0000, v73
	v_pk_fma_f32 v[16:17], v[16:17], v[98:99], v[122:123]
	v_pk_fma_f32 v[14:15], v[14:15], v[96:97], v[120:121]
	v_cvt_pk_bf16_f32 v82, v14, v15
	v_cvt_pk_bf16_f32 v83, v16, v17
	global_store_dwordx2 v10, v[82:83], s[30:31]
	s_add_u32 s30, s30, 0x40000
	s_addc_u32 s31, s31, 0
	s_waitcnt vmcnt(11)
	v_lshlrev_b32_e32 v116, 16, v74
	v_and_b32_e32 v117, 0xffff0000, v74
	v_lshlrev_b32_e32 v118, 16, v75
	v_and_b32_e32 v119, 0xffff0000, v75
	v_pk_fma_f32 v[16:17], v[16:17], v[102:103], v[118:119]
	v_pk_fma_f32 v[14:15], v[14:15], v[100:101], v[116:117]
	v_cvt_pk_bf16_f32 v124, v14, v15
	v_cvt_pk_bf16_f32 v125, v16, v17
	global_store_dwordx2 v10, v[124:125], s[30:31]
	s_add_u32 s30, s30, 0x40000
	s_addc_u32 s31, s31, 0
	s_waitcnt vmcnt(10)
	v_lshlrev_b32_e32 v120, 16, v76
	v_and_b32_e32 v121, 0xffff0000, v76
	v_lshlrev_b32_e32 v122, 16, v77
	v_and_b32_e32 v123, 0xffff0000, v77
	v_pk_fma_f32 v[16:17], v[16:17], v[106:107], v[122:123]
	v_pk_fma_f32 v[14:15], v[14:15], v[104:105], v[120:121]
	v_cvt_pk_bf16_f32 v82, v14, v15
	v_cvt_pk_bf16_f32 v83, v16, v17
	global_store_dwordx2 v10, v[82:83], s[30:31]
	s_add_u32 s30, s30, 0x40000
	s_addc_u32 s31, s31, 0
	s_waitcnt vmcnt(9)
	v_lshlrev_b32_e32 v116, 16, v78
	v_and_b32_e32 v117, 0xffff0000, v78
	v_lshlrev_b32_e32 v118, 16, v79
	v_and_b32_e32 v119, 0xffff0000, v79
	v_pk_fma_f32 v[16:17], v[16:17], v[110:111], v[118:119]
	v_pk_fma_f32 v[14:15], v[14:15], v[108:109], v[116:117]
	v_cvt_pk_bf16_f32 v124, v14, v15
	v_cvt_pk_bf16_f32 v125, v16, v17
	global_store_dwordx2 v10, v[124:125], s[30:31]
	s_add_u32 s30, s30, 0x40000
	s_addc_u32 s31, s31, 0
	s_waitcnt vmcnt(8)
	v_lshlrev_b32_e32 v120, 16, v80
	v_and_b32_e32 v121, 0xffff0000, v80
	v_lshlrev_b32_e32 v122, 16, v81
	v_and_b32_e32 v123, 0xffff0000, v81
	v_pk_fma_f32 v[16:17], v[16:17], v[114:115], v[122:123]
	v_pk_fma_f32 v[14:15], v[14:15], v[112:113], v[120:121]
	v_lshl_or_b32 v8, v8, 7, v3
	v_ashrrev_i32_e32 v9, 31, v8
	v_add_u32_e32 v7, 0xc0, v7
	v_lshlrev_b64 v[8:9], 10, v[8:9]
	v_lshrrev_b32_e32 v4, 3, v4
	v_cmp_le_i32_e32 vcc, s26, v7
	v_lshl_add_u64 v[8:9], s[6:7], 0, v[8:9]
	v_and_b32_e32 v4, 0x3fc, v4
	s_andn2_b64 s[20:21], s[20:21], exec
	s_and_b64 s[30:31], vcc, exec
	v_lshl_add_u64 v[8:9], v[8:9], 0, v[4:5]
	v_add_u32_e32 v1, 0xc0, v1
	s_or_b64 s[20:21], s[20:21], s[30:31]
	global_store_dword v[8:9], v14, off
	global_store_dword v[8:9], v15, off offset:1024
	global_store_dword v[8:9], v16, off offset:2048
	global_store_dword v[8:9], v17, off offset:3072
	s_branch .LBB0_565
